# grid barrier release: every workgroup polls the top-level generation word directly, per-XCD re-broadcast removed
# baseline (speedup 1.0000x reference)
; __device__ __forceinline__ unsigned xb_ld(unsigned* p)              { return __hip_atomic_load(p, __ATOMIC_RELAXED, __HIP_MEMORY_SCOPE_AGENT); }
; __device__ __forceinline__ unsigned xb_add(unsigned* p, unsigned v) { return __hip_atomic_fetch_add(p, v, __ATOMIC_RELAXED, __HIP_MEMORY_SCOPE_AGENT); }
; #define XB_SPIN(cond, bar) do { unsigned _sp = 0; while (cond) { __builtin_amdgcn_s_sleep(1); \
;     if ((++_sp & 255u) == 0u) { if (xb_ld(&(bar)[XB_TMO])) break; if (_sp > XB_SPIN_CAP) { (void)xb_add(&(bar)[XB_TMO], 1u); break; } } } } while (0)
; __device__ __forceinline__ void xcd_barrier(const XcdBarrier& b) {
;     ...
;         const unsigned old = xb_add(&bar[XB_XSUB(b.x)], 1u);
;         const unsigned gen = old / nloc;
;         if (old + 1u == (gen + 1u) * nloc) {
;             __builtin_amdgcn_fence(__ATOMIC_RELEASE, "agent");
;             asm volatile("s_waitcnt vmcnt(0)" ::: "memory");
;             const unsigned og = xb_add(&bar[XB_TOP], 1u);
;             const unsigned tg = og / nx;
;             if (og + 1u == (tg + 1u) * nx) xb_add(&bar[XB_TOPGEN], 1u);
;             else XB_SPIN(xb_ld(&bar[XB_TOPGEN]) == tg, bar);
;             __builtin_amdgcn_fence(__ATOMIC_ACQUIRE, "agent");
;             xb_add(&bar[XB_XGEN(b.x)], 1u);
;             asm volatile("s_waitcnt vmcnt(0)" ::: "memory");
;         } else {
;             XB_SPIN(xb_ld(&bar[XB_XGEN(b.x)]) == gen, bar);
.Lmy_s0_160:
	s_lshl_b32 s6, s81, 8
	v_readlane_b32 s8, v245, 19
	v_readlane_b32 s9, v245, 20
	s_add_u32 s6, s8, s6
	s_addc_u32 s7, s9, 0
	v_mov_b32_e32 v1, 0x1000
	v_mov_b32_e32 v3, 1
	global_atomic_add v3, v1, v3, s[6:7] offset:1024 sc0
	v_cvt_f32_u32_e32 v1, v2
	v_sub_u32_e32 v4, 0, v2
	v_rcp_iflag_f32_e32 v1, v1
	s_nop 0
	v_mul_f32_e32 v1, 0x4f7ffffe, v1
	v_cvt_u32_f32_e32 v1, v1
	v_mul_lo_u32 v4, v4, v1
	v_mul_hi_u32 v4, v1, v4
	v_add_u32_e32 v1, v1, v4
	s_waitcnt vmcnt(0)
	v_mul_hi_u32 v1, v3, v1
	v_mul_lo_u32 v4, v1, v2
	v_sub_u32_e32 v4, v3, v4
	v_add_u32_e32 v5, 1, v1
	v_cmp_ge_u32_e32 vcc, v4, v2
	v_add_u32_e32 v3, 1, v3
	s_nop 0
	v_cndmask_b32_e32 v1, v1, v5, vcc
	v_sub_u32_e32 v5, v4, v2
	v_cndmask_b32_e32 v4, v4, v5, vcc
	v_add_u32_e32 v5, 1, v1
	v_cmp_ge_u32_e32 vcc, v4, v2
	s_nop 1
	v_cndmask_b32_e32 v1, v1, v5, vcc
	v_mul_lo_u32 v4, v2, v1
	v_add_u32_e32 v2, v4, v2
	v_cmp_ne_u32_e32 vcc, v3, v2
	s_and_saveexec_b64 s[8:9], vcc
	s_xor_b64 s[8:9], exec, s[8:9]
	s_cbranch_execz .Lmy_s0_174
	s_waitcnt lgkmcnt(0)
	v_mov_b32_e32 v0, 0
	s_add_u32 s14, s84, 0x1da03600
	s_addc_u32 s15, s85, 0
	global_load_dword v0, v0, s[14:15] sc1
	s_waitcnt vmcnt(0)
	v_cmp_eq_u32_e32 vcc, v0, v1
	s_and_saveexec_b64 s[10:11], vcc
	s_cbranch_execz .Lmy_s0_173
	s_add_u32 s12, s84, 0x1da00300
	s_addc_u32 s13, s85, 0
	s_mov_b32 s26, 1
	s_mov_b64 s[16:17], 0
	v_mov_b32_e32 v0, 0
	s_branch .Lmy_s0_164

; __device__ __forceinline__ unsigned xb_ld(unsigned* p)              { return __hip_atomic_load(p, __ATOMIC_RELAXED, __HIP_MEMORY_SCOPE_AGENT); }
; __device__ __forceinline__ unsigned xb_add(unsigned* p, unsigned v) { return __hip_atomic_fetch_add(p, v, __ATOMIC_RELAXED, __HIP_MEMORY_SCOPE_AGENT); }
; #define XB_SPIN(cond, bar) do { unsigned _sp = 0; while (cond) { __builtin_amdgcn_s_sleep(1); \
;     if ((++_sp & 255u) == 0u) { if (xb_ld(&(bar)[XB_TMO])) break; if (_sp > XB_SPIN_CAP) { (void)xb_add(&(bar)[XB_TMO], 1u); break; } } } } while (0)
; __device__ __forceinline__ void xcd_barrier(const XcdBarrier& b) {
;     ...
;         if (old + 1u == (gen + 1u) * nloc) {
;             __builtin_amdgcn_fence(__ATOMIC_RELEASE, "agent");
;             asm volatile("s_waitcnt vmcnt(0)" ::: "memory");
;             const unsigned og = xb_add(&bar[XB_TOP], 1u);
;             const unsigned tg = og / nx;
;             if (og + 1u == (tg + 1u) * nx) xb_add(&bar[XB_TOPGEN], 1u);
;             else XB_SPIN(xb_ld(&bar[XB_TOPGEN]) == tg, bar);
;             __builtin_amdgcn_fence(__ATOMIC_ACQUIRE, "agent");
;             xb_add(&bar[XB_XGEN(b.x)], 1u);
;             asm volatile("s_waitcnt vmcnt(0)" ::: "memory");
.Lmy_s0_191:
	s_or_b64 exec, exec, s[8:9]
	v_mov_b32_e32 v0, 0x2000
	v_mov_b32_e32 v1, 1
	s_waitcnt vmcnt(0)
	buffer_inv sc1
	s_waitcnt vmcnt(0)

; __device__ __forceinline__ unsigned xb_ld(unsigned* p)              { return __hip_atomic_load(p, __ATOMIC_RELAXED, __HIP_MEMORY_SCOPE_AGENT); }
; __device__ __forceinline__ unsigned xb_add(unsigned* p, unsigned v) { return __hip_atomic_fetch_add(p, v, __ATOMIC_RELAXED, __HIP_MEMORY_SCOPE_AGENT); }
; #define XB_SPIN(cond, bar) do { unsigned _sp = 0; while (cond) { __builtin_amdgcn_s_sleep(1); \
;     if ((++_sp & 255u) == 0u) { if (xb_ld(&(bar)[XB_TMO])) break; if (_sp > XB_SPIN_CAP) { (void)xb_add(&(bar)[XB_TMO], 1u); break; } } } } while (0)
; __device__ __forceinline__ void xcd_barrier(const XcdBarrier& b) {
;     ...
;         const unsigned old = xb_add(&bar[XB_XSUB(b.x)], 1u);
;         const unsigned gen = old / nloc;
;         if (old + 1u == (gen + 1u) * nloc) {
;             __builtin_amdgcn_fence(__ATOMIC_RELEASE, "agent");
;             asm volatile("s_waitcnt vmcnt(0)" ::: "memory");
;             const unsigned og = xb_add(&bar[XB_TOP], 1u);
;             const unsigned tg = og / nx;
;             if (og + 1u == (tg + 1u) * nx) xb_add(&bar[XB_TOPGEN], 1u);
;             else XB_SPIN(xb_ld(&bar[XB_TOPGEN]) == tg, bar);
;             __builtin_amdgcn_fence(__ATOMIC_ACQUIRE, "agent");
;             xb_add(&bar[XB_XGEN(b.x)], 1u);
;             asm volatile("s_waitcnt vmcnt(0)" ::: "memory");
;         } else {
;             XB_SPIN(xb_ld(&bar[XB_XGEN(b.x)]) == gen, bar);
.LBB0_639:
	s_lshl_b32 s4, s81, 8
	v_readlane_b32 s6, v245, 19
	v_readlane_b32 s7, v245, 20
	s_add_u32 s4, s6, s4
	s_addc_u32 s5, s7, 0
	v_mov_b32_e32 v1, 0x1000
	v_mov_b32_e32 v3, 1
	global_atomic_add v3, v1, v3, s[4:5] offset:1024 sc0
	v_cvt_f32_u32_e32 v1, v2
	v_sub_u32_e32 v4, 0, v2
	v_rcp_iflag_f32_e32 v1, v1
	s_nop 0
	v_mul_f32_e32 v1, 0x4f7ffffe, v1
	v_cvt_u32_f32_e32 v1, v1
	v_mul_lo_u32 v4, v4, v1
	v_mul_hi_u32 v4, v1, v4
	v_add_u32_e32 v1, v1, v4
	s_waitcnt vmcnt(0)
	v_mul_hi_u32 v1, v3, v1
	v_mul_lo_u32 v4, v1, v2
	v_sub_u32_e32 v4, v3, v4
	v_add_u32_e32 v5, 1, v1
	v_cmp_ge_u32_e32 vcc, v4, v2
	v_add_u32_e32 v3, 1, v3
	s_nop 0
	v_cndmask_b32_e32 v1, v1, v5, vcc
	v_sub_u32_e32 v5, v4, v2
	v_cndmask_b32_e32 v4, v4, v5, vcc
	v_add_u32_e32 v5, 1, v1
	v_cmp_ge_u32_e32 vcc, v4, v2
	s_nop 1
	v_cndmask_b32_e32 v1, v1, v5, vcc
	v_mul_lo_u32 v4, v2, v1
	v_add_u32_e32 v2, v4, v2
	v_cmp_ne_u32_e32 vcc, v3, v2
	s_and_saveexec_b64 s[6:7], vcc
	s_xor_b64 s[6:7], exec, s[6:7]
	s_cbranch_execz .LBB0_653
	s_waitcnt lgkmcnt(0)
	v_mov_b32_e32 v0, 0
	s_add_u32 s12, s84, 0x1da03600
	s_addc_u32 s13, s85, 0
	global_load_dword v0, v0, s[12:13] sc1
	s_waitcnt vmcnt(0)
	v_cmp_eq_u32_e32 vcc, v0, v1
	s_and_saveexec_b64 s[8:9], vcc
	s_cbranch_execz .LBB0_652
	s_add_u32 s10, s84, 0x1da00300
	s_addc_u32 s11, s85, 0
	s_mov_b32 s24, 1
	s_mov_b64 s[14:15], 0
	v_mov_b32_e32 v0, 0
	s_branch .LBB0_643

; __device__ __forceinline__ unsigned xb_ld(unsigned* p)              { return __hip_atomic_load(p, __ATOMIC_RELAXED, __HIP_MEMORY_SCOPE_AGENT); }
; __device__ __forceinline__ unsigned xb_add(unsigned* p, unsigned v) { return __hip_atomic_fetch_add(p, v, __ATOMIC_RELAXED, __HIP_MEMORY_SCOPE_AGENT); }
; #define XB_SPIN(cond, bar) do { unsigned _sp = 0; while (cond) { __builtin_amdgcn_s_sleep(1); \
;     if ((++_sp & 255u) == 0u) { if (xb_ld(&(bar)[XB_TMO])) break; if (_sp > XB_SPIN_CAP) { (void)xb_add(&(bar)[XB_TMO], 1u); break; } } } } while (0)
; __device__ __forceinline__ void xcd_barrier(const XcdBarrier& b) {
;     ...
;         if (old + 1u == (gen + 1u) * nloc) {
;             __builtin_amdgcn_fence(__ATOMIC_RELEASE, "agent");
;             asm volatile("s_waitcnt vmcnt(0)" ::: "memory");
;             const unsigned og = xb_add(&bar[XB_TOP], 1u);
;             const unsigned tg = og / nx;
;             if (og + 1u == (tg + 1u) * nx) xb_add(&bar[XB_TOPGEN], 1u);
;             else XB_SPIN(xb_ld(&bar[XB_TOPGEN]) == tg, bar);
;             __builtin_amdgcn_fence(__ATOMIC_ACQUIRE, "agent");
;             xb_add(&bar[XB_XGEN(b.x)], 1u);
;             asm volatile("s_waitcnt vmcnt(0)" ::: "memory");
.LBB0_670:
	s_or_b64 exec, exec, s[6:7]
	v_mov_b32_e32 v0, 0x2000
	v_mov_b32_e32 v1, 1
	s_waitcnt vmcnt(0)
	buffer_inv sc1
	s_waitcnt vmcnt(0)
